# layer-0 P1 barrier without invalidate (every P2/P3 load in layer 0 is a first touch since kernel start); site-7 full-path invalidates only in fallback mode
# speedup vs baseline: 1.0082x; 1.0055x over previous
.LBB0_211:
	s_or_b64 exec, exec, s[8:9]
	s_add_i32 s82, s6, 0x900
	s_lshl_b64 s[6:7], s[82:83], 2
	s_add_u32 s6, s42, s6
	s_addc_u32 s7, s43, s7
	v_mov_b64_e32 v[0:1], s[6:7]
	s_waitcnt vmcnt(0) lgkmcnt(0)
	s_cmp_lg_u32 s100, 0
	s_cbranch_scc1 .Lninv_7b
	buffer_inv sc1
.Lninv_7b:
	flat_atomic_add v[0:1], v228
	s_waitcnt vmcnt(0)

.LBB0_375:
	s_lshl_b32 s6, s6, 6
	s_add_i32 s82, s6, 0x500
	s_lshl_b64 s[8:9], s[82:83], 2
	s_add_u32 s8, s42, s8
	s_addc_u32 s9, s43, s9
	v_mov_b64_e32 v[4:5], s[8:9]
	flat_atomic_add v3, v[4:5], v228 sc0
	v_cvt_f32_u32_e32 v1, v2
	v_sub_u32_e32 v4, 0, v2
	v_rcp_iflag_f32_e32 v1, v1
	s_nop 0
	v_mul_f32_e32 v1, 0x4f7ffffe, v1
	v_cvt_u32_f32_e32 v1, v1
	v_mul_lo_u32 v4, v4, v1
	v_mul_hi_u32 v4, v1, v4
	v_add_u32_e32 v1, v1, v4
	s_waitcnt vmcnt(0) lgkmcnt(0)
	v_mul_hi_u32 v1, v3, v1
	v_mul_lo_u32 v4, v1, v2
	v_sub_u32_e32 v4, v3, v4
	v_cmp_ge_u32_e32 vcc, v4, v2
	v_add_u32_e32 v5, 1, v1
	s_nop 0
	v_cndmask_b32_e32 v1, v1, v5, vcc
	v_sub_u32_e32 v5, v4, v2
	v_cndmask_b32_e32 v4, v4, v5, vcc
	v_cmp_ge_u32_e32 vcc, v4, v2
	v_add_u32_e32 v4, 1, v1
	s_nop 0
	v_cndmask_b32_e32 v1, v1, v4, vcc
	v_add_u32_e32 v4, 1, v3
	v_mad_u64_u32 v[2:3], s[8:9], v2, v1, v[2:3]
	v_cmp_ne_u32_e32 vcc, v4, v2
	s_and_saveexec_b64 s[8:9], vcc
	s_xor_b64 s[8:9], exec, s[8:9]
	s_cbranch_execz .LBB0_388
	s_cmp_eq_u32 s100, 0
	s_cbranch_scc1 .Lnf_1
	s_cmp_lg_u32 s101, 1
	s_cbranch_scc1 .Lnf_1
	s_add_i32 s82, s6, 0x900
	s_lshl_b64 s[10:11], s[82:83], 2
	s_add_u32 s10, s42, s10
	s_addc_u32 s11, s43, s11
	v_mov_b64_e32 v[2:3], s[10:11]
.Lxg_1:
	flat_load_dword v234, v[2:3] sc1
	s_waitcnt vmcnt(0) lgkmcnt(0)
	v_cmp_gt_u32_e32 vcc, v234, v1
	s_cbranch_vccz .Lxg_1
	s_waitcnt vmcnt(0)
	s_branch .LBB0_404

.LBB0_388:
	s_andn2_saveexec_b64 s[8:9], s[8:9]
	s_cbranch_execz .LBB0_404
	s_cmp_eq_u32 s100, 0
	s_cbranch_scc1 .Lfl_1
	s_cmp_lg_u32 s101, 1
	s_cbranch_scc1 .Lfl_1
	s_add_i32 s82, s6, 0x900
	s_lshl_b64 s[10:11], s[82:83], 2
	s_add_u32 s10, s42, s10
	s_addc_u32 s11, s43, s11
	v_mov_b64_e32 v[0:1], s[10:11]
	flat_atomic_add v[0:1], v228
	s_waitcnt vmcnt(0)
	s_branch .LBB0_404

.LBB0_1400:
	s_or_b64 exec, exec, s[10:11]
	s_waitcnt vmcnt(0) lgkmcnt(0)
	s_cmp_lg_u32 s100, 0
	s_cbranch_scc1 .Lninv_7a
	buffer_inv sc1
.Lninv_7a:
	s_waitcnt vmcnt(0)
.LBB0_1401:
	s_andn2_saveexec_b64 s[8:9], s[8:9]
	s_cbranch_execnz .LBB0_1402
